# speedup vs baseline: 1.0113x; 1.0113x over previous
; #define LAS __attribute__((address_space(3)))
; DI unsigned pk2(float lo, float hi) { const f32x2 v = {lo, hi}; return __builtin_bit_cast(unsigned, __builtin_convertvector(v, bf16v2)); }
; DI void norm_row(const float* xrow, const float* g, bf16_t* hrow, float* xout, int lane, bool zero) {
;     const f32x4* xr = (const f32x4*)xrow + lane;
;     f32x4 v[8]; float s = 0.f;
; #pragma unroll
;     for (int j = 0; j < 8; ++j) { v[j] = zero ? (f32x4){0.f, 0.f, 0.f, 0.f} : xr[64 * j]; s += (v[j].x * v[j].x + v[j].y * v[j].y) + (v[j].z * v[j].z + v[j].w * v[j].w); }
;     s = wave_sum(s);
;     const float rstd = 1.0f / sqrtf(s * (1.0f / DM) + 1e-6f);
;     if (xout) {
; #pragma unroll
;         for (int j = 0; j < 8; ++j) ((f32x4*)xout)[lane + 64 * j] = v[j];
;     }
; #pragma unroll
;     for (int j = 0; j < 8; ++j) { const f32x4 gv = ((const f32x4*)g)[lane + 64 * j]; const f32x4 o = v[j] * rstd * gv; u32x2 w; w.x = pk2(o.x, o.y); w.y = pk2(o.z, o.w); ((u32x2*)hrow)[lane + 64 * j] = w; }
; template <int K>
; DI void skinny_res(LAS unsigned char* lds, const bf16_t* A, const bf16_t* Wt, float* X, int G, int bid, const int wave, unsigned* counter, const float* gn, bf16_t* H) {
;     ...
;     if (gn) {
;         asm volatile("s_waitcnt vmcnt(0)" ::: "memory");
;         __syncthreads();
;         LAS unsigned* flag = (LAS unsigned*)(lds + 32768);
;         if (tid == 0) { const unsigned old = __hip_atomic_fetch_add(counter, 1u, __ATOMIC_RELAXED, __HIP_MEMORY_SCOPE_AGENT); *flag = (old == (unsigned)G - 1u) ? 1u : 0u; }
;         __syncthreads();
;         if (*flag) {
;             __builtin_amdgcn_fence(__ATOMIC_ACQUIRE, "agent");
;             for (int r = wave; r < DB; r += NWAVES) norm_row(X + (size_t)(MPROMPT + r) * DM, gn, H + (size_t)(MPROMPT + r) * DM, nullptr, lane, false);
.LBB0_1075:
	s_or_b64 exec, exec, s[36:37]
	s_waitcnt lgkmcnt(0)
	s_barrier
	ds_read_b32 v0, v161 offset:32768
	s_waitcnt lgkmcnt(0)
	v_cmp_eq_u32_e32 vcc, 0, v0
	s_cbranch_vccnz .LBB0_1079
	v_readlane_b32 s6, v254, 16
	v_readlane_b32 s7, v254, 17
	s_andn2_b64 vcc, exec, s[6:7]
	s_waitcnt vmcnt(0)
	buffer_inv sc1
	s_cbranch_vccnz .LBB0_1079
	v_and_b32_e32 v0, 64, v245
	v_add_u32_e32 v0, 64, v0
	v_xor_b32_e32 v1, 1, v245
	v_cmp_lt_i32_e32 vcc, v1, v0
	v_ashrrev_i32_e32 v17, 31, v16
	s_mov_b64 s[14:15], 0x8000
	v_cndmask_b32_e32 v1, v245, v1, vcc
	v_lshlrev_b32_e32 v47, 2, v1
	v_xor_b32_e32 v1, 2, v245
	v_cmp_lt_i32_e32 vcc, v1, v0
	s_nop 1
	v_cndmask_b32_e32 v1, v245, v1, vcc
	v_lshlrev_b32_e32 v48, 2, v1
	v_xor_b32_e32 v1, 4, v245
	v_cmp_lt_i32_e32 vcc, v1, v0
	s_nop 1
	v_cndmask_b32_e32 v1, v245, v1, vcc
	v_lshlrev_b32_e32 v49, 2, v1
	v_xor_b32_e32 v1, 8, v245
	v_cmp_lt_i32_e32 vcc, v1, v0
	s_nop 1
	v_cndmask_b32_e32 v1, v245, v1, vcc
	v_lshlrev_b32_e32 v50, 2, v1
	v_xor_b32_e32 v1, 16, v245
	v_cmp_lt_i32_e32 vcc, v1, v0
	s_nop 1
	v_cndmask_b32_e32 v1, v245, v1, vcc
	v_lshlrev_b32_e32 v51, 2, v1
	v_xor_b32_e32 v1, 32, v245
	v_cmp_lt_i32_e32 vcc, v1, v0
	s_nop 1
	v_cndmask_b32_e32 v0, v245, v1, vcc
	v_lshlrev_b32_e32 v52, 2, v0
	v_lshlrev_b64 v[0:1], 4, v[16:17]
	v_lshl_add_u64 v[32:33], s[0:1], 0, v[0:1]
	s_mov_b64 s[0:1], 0x1000
	v_lshl_add_u64 v[34:35], v[32:33], 0, s[0:1]
	s_mov_b64 s[0:1], 0x1400
	v_lshl_add_u64 v[36:37], v[32:33], 0, s[0:1]
	s_mov_b64 s[0:1], 0x1800
	v_lshl_add_u64 v[38:39], v[32:33], 0, s[0:1]
	s_mov_b64 s[0:1], 0x1c00
	v_lshl_add_u64 v[40:41], v[32:33], 0, s[0:1]
	v_readlane_b32 s0, v254, 35
	v_readlane_b32 s1, v254, 36
	s_nop 1
	v_lshl_add_u64 v[42:43], v[16:17], 3, s[0:1]
	v_readlane_b32 s0, v254, 37
	v_readlane_b32 s1, v254, 38
	s_nop 1
	v_lshl_add_u64 v[44:45], s[0:1], 0, v[0:1]
	v_readlane_b32 s0, v254, 20
	global_load_dwordx4 v[64:67], v[32:33], off
	global_load_dwordx4 v[68:71], v[32:33], off offset:1024
	global_load_dwordx4 v[72:75], v[32:33], off offset:2048
	global_load_dwordx4 v[76:79], v[32:33], off offset:3072
	global_load_dwordx4 v[80:83], v[34:35], off
	global_load_dwordx4 v[84:87], v[36:37], off
	global_load_dwordx4 v[88:91], v[38:39], off
	global_load_dwordx4 v[92:95], v[40:41], off
.LBB0_1078:
	v_lshl_add_u64 v[8:9], s[68:69], 0, v[44:45]
	v_add_co_u32_e32 v0, vcc, 0x19400000, v8
	s_mov_b32 s1, 0x19401000
	s_nop 0
	v_addc_co_u32_e32 v1, vcc, 0, v9, vcc
	global_load_dwordx4 v[28:31], v[0:1], off
	global_load_dwordx4 v[4:7], v[0:1], off offset:1024
	v_add_co_u32_e32 v8, vcc, s1, v8
	s_mov_b32 s1, 0x1b600000
	s_nop 0
	v_addc_co_u32_e32 v9, vcc, 0, v9, vcc
	s_add_i32 s0, s0, 8
	s_cmp_lt_u32 s0, 24
	s_waitcnt vmcnt(1)
	v_mov_b32_e32 v10, v29
	s_waitcnt vmcnt(0)
	v_mov_b32_e32 v11, v5
	v_mov_b32_e32 v2, v28
	v_mov_b32_e32 v3, v4
	v_pk_mul_f32 v[10:11], v[10:11], v[10:11]
	v_mov_b32_e32 v12, v31
	v_mov_b32_e32 v13, v7
	v_pk_fma_f32 v[2:3], v[2:3], v[2:3], v[10:11]
	v_mov_b32_e32 v10, v30
	v_mov_b32_e32 v11, v6
	v_pk_mul_f32 v[12:13], v[12:13], v[12:13]
	s_nop 0
	v_pk_fma_f32 v[10:11], v[10:11], v[10:11], v[12:13]
	global_load_dwordx4 v[12:15], v[0:1], off offset:2048
	v_pk_add_f32 v[10:11], v[2:3], v[10:11]
	s_waitcnt vmcnt(0)
	v_pk_mul_f32 v[2:3], v[14:15], v[14:15]
	v_pk_mul_f32 v[16:17], v[12:13], v[12:13]
	v_pk_add_f32 v[10:11], v[10:11], v[10:11] op_sel:[0,1] op_sel_hi:[1,0]
	v_pk_mov_b32 v[18:19], v[16:17], v[2:3] op_sel:[1,0]
	v_mov_b32_e32 v17, v3
	v_pk_add_f32 v[20:21], v[18:19], v[16:17]
	global_load_dwordx4 v[0:3], v[0:1], off offset:3072
	v_pk_add_f32 v[20:21], v[20:21], v[20:21] op_sel:[0,1] op_sel_hi:[1,0]
	global_load_dwordx4 v[16:19], v[8:9], off
	s_waitcnt vmcnt(0)
	v_mul_f32_e32 v22, v16, v16
	v_mul_f32_e32 v23, v17, v17
	v_mov_b32_e32 v11, v22
	v_mov_b32_e32 v21, v23
	v_pk_add_f32 v[10:11], v[10:11], v[20:21]
	v_mul_f32_e32 v20, v1, v1
	v_mul_f32_e32 v22, v3, v3
	v_mul_f32_e32 v24, v18, v18
	v_mul_f32_e32 v25, v19, v19
	v_pk_fma_f32 v[20:21], v[0:1], v[0:1], v[20:21] op_sel_hi:[1,1,0]
	v_pk_fma_f32 v[22:23], v[2:3], v[2:3], v[22:23] op_sel_hi:[1,1,0]
	v_mov_b32_e32 v21, v24
	v_mov_b32_e32 v23, v25
	global_load_dwordx4 v[24:27], v[8:9], off offset:1024
	v_pk_add_f32 v[20:21], v[20:21], v[22:23]
	s_nop 0
	v_pk_add_f32 v[54:55], v[10:11], v[20:21]
	s_waitcnt vmcnt(0)
	v_pk_mul_f32 v[10:11], v[26:27], v[26:27]
	v_pk_mul_f32 v[20:21], v[24:25], v[24:25]
	v_pk_add_f32 v[54:55], v[54:55], v[54:55] op_sel:[0,1] op_sel_hi:[1,0]
	v_pk_mov_b32 v[22:23], v[20:21], v[10:11] op_sel:[1,0]
	v_mov_b32_e32 v21, v11
	v_pk_add_f32 v[56:57], v[22:23], v[20:21]
	global_load_dwordx4 v[20:23], v[8:9], off offset:2048
	s_nop 0
	global_load_dwordx4 v[8:11], v[8:9], off offset:3072
	v_pk_add_f32 v[56:57], v[56:57], v[56:57] op_sel:[0,1] op_sel_hi:[1,0]
	s_waitcnt vmcnt(0)
; DI unsigned pk2(float lo, float hi) { const f32x2 v = {lo, hi}; return __builtin_bit_cast(unsigned, __builtin_convertvector(v, bf16v2)); }
; DI void norm_row(const float* xrow, const float* g, bf16_t* hrow, float* xout, int lane, bool zero) {
;     ...
;     s = wave_sum(s);
;     const float rstd = 1.0f / sqrtf(s * (1.0f / DM) + 1e-6f);
;     if (xout) {
; #pragma unroll
;         for (int j = 0; j < 8; ++j) ((f32x4*)xout)[lane + 64 * j] = v[j];
;     }
; #pragma unroll
;     for (int j = 0; j < 8; ++j) { const f32x4 gv = ((const f32x4*)g)[lane + 64 * j]; const f32x4 o = v[j] * rstd * gv; u32x2 w; w.x = pk2(o.x, o.y); w.y = pk2(o.z, o.w); ((u32x2*)hrow)[lane + 64 * j] = w; }
	v_mul_f32_e32 v46, v8, v8
	v_mul_f32_e32 v53, v9, v9
	v_mov_b32_e32 v55, v46
	v_mov_b32_e32 v57, v53
	v_mul_f32_e32 v46, v21, v21
	v_mul_f32_e32 v58, v10, v10
	v_pk_add_f32 v[54:55], v[54:55], v[56:57]
	v_pk_fma_f32 v[56:57], v[20:21], v[20:21], v[46:47] op_sel_hi:[1,1,0]
	v_mul_f32_e32 v46, v23, v23
	v_mul_f32_e32 v60, v11, v11
	v_mov_b32_e32 v57, v58
	v_pk_fma_f32 v[58:59], v[22:23], v[22:23], v[46:47] op_sel_hi:[1,1,0]
	s_nop 0
	v_mov_b32_e32 v59, v60
	v_pk_add_f32 v[56:57], v[56:57], v[58:59]
	s_nop 0
	v_pk_add_f32 v[54:55], v[54:55], v[56:57]
	s_nop 0
	v_add_f32_e32 v46, v54, v55
	ds_bpermute_b32 v53, v47, v46
	s_waitcnt lgkmcnt(0)
	v_add_f32_e32 v46, v46, v53
	ds_bpermute_b32 v53, v48, v46
	s_waitcnt lgkmcnt(0)
	v_add_f32_e32 v46, v46, v53
	ds_bpermute_b32 v53, v49, v46
	s_waitcnt lgkmcnt(0)
	v_add_f32_e32 v46, v46, v53
	ds_bpermute_b32 v53, v50, v46
	s_waitcnt lgkmcnt(0)
	v_add_f32_e32 v46, v46, v53
	ds_bpermute_b32 v53, v51, v46
	s_waitcnt lgkmcnt(0)
	v_add_f32_e32 v46, v46, v53
	ds_bpermute_b32 v53, v52, v46
	s_waitcnt lgkmcnt(0)
	v_add_f32_e32 v46, v46, v53
	v_fmamk_f32 v46, v46, 0x3a000000, v242
	v_cmp_gt_f32_e32 vcc, s33, v46
	v_mul_f32_e32 v53, 0x4f800000, v46
	s_nop 0
	v_cndmask_b32_e32 v46, v46, v53, vcc
	v_sqrt_f32_e32 v53, v46
	s_nop 0
	v_add_u32_e32 v54, -1, v53
	v_fma_f32 v55, -v54, v53, v46
	v_cmp_ge_f32_e64 s[36:37], 0, v55
	v_add_u32_e32 v55, 1, v53
	s_nop 0
	v_cndmask_b32_e64 v54, v53, v54, s[36:37]
	v_fma_f32 v53, -v55, v53, v46
	v_cmp_lt_f32_e64 s[36:37], 0, v53
	s_nop 1
	v_cndmask_b32_e64 v53, v54, v55, s[36:37]
	v_mul_f32_e32 v54, 0x37800000, v53
	v_cndmask_b32_e32 v53, v53, v54, vcc
	v_cmp_class_f32_e32 vcc, v46, v243
	s_nop 1
	v_cndmask_b32_e32 v46, v53, v46, vcc
	v_div_scale_f32 v53, s[6:7], v46, v46, 1.0
	v_rcp_f32_e32 v54, v53
	s_mov_b64 s[6:7], 0x10000
	v_lshl_add_u64 v[44:45], v[44:45], 0, s[6:7]
	v_fma_f32 v55, -v53, v54, 1.0
	v_fmac_f32_e32 v54, v55, v54
	v_div_scale_f32 v55, vcc, 1.0, v46, 1.0
	v_mul_f32_e32 v56, v55, v54
	v_fma_f32 v57, -v53, v56, v55
	v_fmac_f32_e32 v56, v57, v54
	v_fma_f32 v53, -v53, v56, v55
	v_div_fmas_f32 v53, v53, v54, v56
	s_nop 1
	v_mov_b64_e32 v[54:55], v[64:65]
	v_mov_b64_e32 v[56:57], v[66:67]
	v_div_fixup_f32 v46, v53, v46, 1.0
	v_pk_mul_f32 v[28:29], v[28:29], v[46:47] op_sel_hi:[1,0]
	v_pk_mul_f32 v[30:31], v[30:31], v[46:47] op_sel_hi:[1,0]
	v_pk_mul_f32 v[4:5], v[4:5], v[46:47] op_sel_hi:[1,0]
	v_pk_mul_f32 v[6:7], v[6:7], v[46:47] op_sel_hi:[1,0]
	v_pk_mul_f32 v[12:13], v[12:13], v[46:47] op_sel_hi:[1,0]
	v_pk_mul_f32 v[14:15], v[14:15], v[46:47] op_sel_hi:[1,0]
	v_pk_mul_f32 v[0:1], v[0:1], v[46:47] op_sel_hi:[1,0]
	v_pk_mul_f32 v[2:3], v[2:3], v[46:47] op_sel_hi:[1,0]
	v_pk_mul_f32 v[28:29], v[54:55], v[28:29]
	v_pk_mul_f32 v[56:57], v[56:57], v[30:31]
	v_cvt_pk_bf16_f32 v30, v28, v29
	v_lshl_add_u64 v[28:29], s[68:69], 0, v[42:43]
	v_add_co_u32_e32 v28, vcc, s1, v28
	v_cvt_pk_bf16_f32 v31, v56, v57
	s_nop 0
	v_addc_co_u32_e32 v29, vcc, 0, v29, vcc
	global_store_dwordx2 v[28:29], v[30:31], off
	s_nop 1
	v_mov_b64_e32 v[54:55], v[68:69]
	v_mov_b64_e32 v[56:57], v[70:71]
	v_lshl_add_u64 v[42:43], v[42:43], 0, s[14:15]
	v_pk_mul_f32 v[6:7], v[56:57], v[6:7]
	v_pk_mul_f32 v[4:5], v[54:55], v[4:5]
	s_nop 0
	v_cvt_pk_bf16_f32 v4, v4, v5
	v_cvt_pk_bf16_f32 v5, v6, v7
	global_store_dwordx2 v[28:29], v[4:5], off offset:512
	s_nop 1
	v_mov_b64_e32 v[4:5], v[72:73]
	v_mov_b64_e32 v[6:7], v[74:75]
	v_pk_mul_f32 v[6:7], v[6:7], v[14:15]
	v_pk_mul_f32 v[4:5], v[4:5], v[12:13]
	s_nop 0
	v_cvt_pk_bf16_f32 v4, v4, v5
	v_cvt_pk_bf16_f32 v5, v6, v7
	global_store_dwordx2 v[28:29], v[4:5], off offset:1024
	s_nop 1
	v_mov_b64_e32 v[4:5], v[76:77]
	v_mov_b64_e32 v[6:7], v[78:79]
	v_pk_mul_f32 v[2:3], v[6:7], v[2:3]
	v_pk_mul_f32 v[0:1], v[4:5], v[0:1]
	v_pk_mul_f32 v[4:5], v[16:17], v[46:47] op_sel_hi:[1,0]
	v_cvt_pk_bf16_f32 v0, v0, v1
	v_cvt_pk_bf16_f32 v1, v2, v3
	global_store_dwordx2 v[28:29], v[0:1], off offset:1536
	s_nop 1
	v_mov_b64_e32 v[0:1], v[80:81]
	v_mov_b64_e32 v[2:3], v[82:83]
	v_pk_mul_f32 v[6:7], v[18:19], v[46:47] op_sel_hi:[1,0]
	v_pk_mul_f32 v[0:1], v[0:1], v[4:5]
	v_pk_mul_f32 v[2:3], v[2:3], v[6:7]
	v_cvt_pk_bf16_f32 v0, v0, v1
	v_cvt_pk_bf16_f32 v1, v2, v3
	global_store_dwordx2 v[28:29], v[0:1], off offset:2048
	s_nop 1
	v_mov_b64_e32 v[0:1], v[84:85]
	v_mov_b64_e32 v[2:3], v[86:87]
	v_pk_mul_f32 v[4:5], v[24:25], v[46:47] op_sel_hi:[1,0]
	v_pk_mul_f32 v[6:7], v[26:27], v[46:47] op_sel_hi:[1,0]
	v_pk_mul_f32 v[0:1], v[0:1], v[4:5]
	v_pk_mul_f32 v[2:3], v[2:3], v[6:7]
	v_cvt_pk_bf16_f32 v0, v0, v1
	v_cvt_pk_bf16_f32 v1, v2, v3
	global_store_dwordx2 v[28:29], v[0:1], off offset:2560
	s_nop 1
	v_mov_b64_e32 v[0:1], v[88:89]
	v_mov_b64_e32 v[2:3], v[90:91]
	v_pk_mul_f32 v[4:5], v[20:21], v[46:47] op_sel_hi:[1,0]
	v_pk_mul_f32 v[6:7], v[22:23], v[46:47] op_sel_hi:[1,0]
	v_pk_mul_f32 v[0:1], v[4:5], v[0:1]
	v_pk_mul_f32 v[2:3], v[6:7], v[2:3]
	v_cvt_pk_bf16_f32 v0, v0, v1
	v_cvt_pk_bf16_f32 v1, v2, v3
	global_store_dwordx2 v[28:29], v[0:1], off offset:3072
	s_nop 1
	v_mov_b64_e32 v[0:1], v[92:93]
	v_mov_b64_e32 v[2:3], v[94:95]
	v_pk_mul_f32 v[4:5], v[8:9], v[46:47] op_sel_hi:[1,0]
	v_pk_mul_f32 v[6:7], v[10:11], v[46:47] op_sel_hi:[1,0]
	v_pk_mul_f32 v[0:1], v[4:5], v[0:1]
	v_pk_mul_f32 v[2:3], v[6:7], v[2:3]
	v_cvt_pk_bf16_f32 v0, v0, v1
	v_cvt_pk_bf16_f32 v1, v2, v3
	global_store_dwordx2 v[28:29], v[0:1], off offset:3584
	s_cbranch_scc1 .LBB0_1078
